# extra grid barrier between the QK GEMM and the V^T GEMM (workgroups of an XCD start the V^T GEMM in step), on top of v148
# baseline (speedup 1.0000x reference)
; __global__ void __launch_bounds__(NWAVES * 64, 2) fwd_megakernel(Args args) {
;     ...
;         if (j != 2 && j != 6) xcd_barrier(xbar);
.LBB0_643:
	s_cmp_eq_u32 s39, 6
	s_cbranch_scc1 .LBB0_215
	s_branch .LBB0_853

; #define PG8_WAIT_V(n) asm volatile("s_waitcnt vmcnt(" #n ")" ::: "memory")
; #define PG8_BAR __builtin_amdgcn_s_barrier()
; __device__ __forceinline__ void gemm_phase(LAS unsigned char* lds, const Gemm g, const StaticOrder& S, const Epi& E) {
;     ...
;     PG8_WAIT_V(0);
;     PG8_BAR;
; __global__ void __launch_bounds__(NWAVES * 64, 2) fwd_megakernel(Args args) {
;     ...
;         if (j != 2 && j != 6) xcd_barrier(xbar);
.LBB0_852:
	s_waitcnt vmcnt(0)
	v_readlane_b32 s72, v250, 34
	v_readlane_b32 s94, v248, 29
	v_readlane_b32 s48, v248, 22
	v_readlane_b32 s30, v248, 26
	v_readlane_b32 s73, v250, 35
	s_mov_b32 s47, s6
	s_mov_b32 s68, s7
	v_readlane_b32 s76, v248, 28
	v_readlane_b32 s95, v248, 30
	v_readlane_b32 s49, v248, 23
	v_readlane_b32 s77, v248, 31
	v_readlane_b32 s88, v248, 32
	v_readlane_b32 s21, v248, 24
	v_readlane_b32 s24, v248, 25
	v_readlane_b32 s31, v248, 27
	s_mov_b32 s25, 0x7f800000
	s_mov_b32 s26, 0x3f2aaaab
	s_mov_b32 s28, 0x3f317218
	s_mov_b32 s38, 0x33800000
	v_readlane_b32 s39, v248, 33
	s_mov_b32 s46, 0xbfb8aa3b
	s_barrier
	s_cmp_eq_u32 s39, 6
	s_cbranch_scc1 .LBB0_215
